# within-XCD split (bit 3), same GEMM-first group in phases 2 and 3 (run 1)
# speedup vs baseline: 1.0033x; 1.0028x over previous
;     __device__ bool next(int i, Unit& u) const { const int L = i * G + c; if (L >= 256) return false; u.pm = L; u.pn = L >> 3; return true; }
; #define GATES_ROUNDS(R0, R1) do { pg8::Gemm g{(const bf16_t*)(ws + WS_XB), (const bf16_t*)(ws + WS_WIN) + (size_t)NPROJ * 1024, 1024, 1024, 1024}; pg8::RoundRange S; S.base.init(MROWS, 2048, G, bx); S.r0 = (R0); S.r1 = (R1); \
;         Epi<EM_GATES> E{ws, nullptr, nullptr, nullptr, nullptr, 0, lds}; pg8::gemm_phase(lds, g, S, E, wave); } while (0)
;     __device__ bool next(int i, Unit& u) const {
;         const long L = (long)i * G + c; if (L >= nwg) return false;
;         int wgid = (int)L; { const int q = nwg / NXCD, r = nwg % NXCD, xcd = wgid % NXCD, off = wgid / NXCD; wgid = (xcd < r ? xcd * (q + 1) : r * (q + 1) + (xcd - r) * q) + off; }
;         const int nig = WGM * nN, gid = wgid / nig, fm = gid * WGM, gsz = (nM - fm) < WGM ? (nM - fm) : WGM;
;         u.pm = fm + ((wgid % nig) % gsz); u.pn = (wgid % nig) / gsz; return true;
;     }
;     __device__ bool next(int i, Unit& u) const { if (r0 + i >= r1) return false; return base.next(r0 + i, u); }
; __global__ void __launch_bounds__(NTHR, 2) fwd_megakernel(Prm P) {
;     ...
;     if (IN(3)) {
;         if (!(bx & 1)) GATES_ROUNDS(2, 4);
.LBB0_791:
	v_readlane_b32 s8, v255, 3
	s_cmp_lt_i32 s8, 4
	s_cselect_b64 s[6:7], -1, 0
	s_and_b64 s[4:5], s[6:7], s[4:5]
	v_readlane_b32 s9, v255, 4
	v_readlane_b32 s10, v255, 5
	v_readlane_b32 s11, v255, 6
	v_writelane_b32 v255, s4, 16
	s_andn2_b64 vcc, exec, s[4:5]
	s_nop 0
	v_writelane_b32 v255, s5, 17
	s_cbranch_vccnz .LBB0_870
	s_bitcmp0_b32 s66, 3
	s_cselect_b64 s[4:5], -1, 0
	v_writelane_b32 v255, s4, 18
	s_and_b64 vcc, exec, s[4:5]
	s_nop 0
	v_writelane_b32 v255, s5, 19
	s_cbranch_vccnz .LBB0_811
	v_readlane_b32 s4, v255, 1
	v_readlane_b32 s5, v255, 2
	s_ashr_i32 s5, s4, 31
	s_lshl_b64 s[6:7], s[4:5], 1
	s_ashr_i32 s5, s66, 31
	v_mbcnt_lo_u32_b32 v0, -1, 0
	v_mbcnt_hi_u32_b32 v0, -1, v0
	v_readlane_b32 s2, v255, 9
	s_add_u32 s6, s6, s66
	s_addc_u32 s7, s7, s5
	v_add_u32_e32 v14, s2, v0
	v_mov_b64_e32 v[0:1], 0x3ff
	v_cmp_gt_i64_e32 vcc, s[6:7], v[0:1]
	s_cbranch_vccnz .LBB0_811
	s_ashr_i32 s2, s6, 31
	s_lshr_b32 s2, s2, 29
	s_add_i32 s8, s6, s2
	s_and_b32 s2, s8, -8
	s_sub_i32 s2, s6, s2
	s_cmp_gt_i32 s2, -1
	s_cbranch_scc0 .LBB0_796
	s_lshl_b32 s9, s2, 7
	s_ashr_i32 s6, s8, 3
	s_cbranch_execz .LBB0_797
	s_branch .LBB0_798
